# in-projection GEMM runs 5 full rounds; its half round (128 tiles) moved into the D1 phase: WGs 0-127 run the sixth tile then one D1 item per wave, WGs 128-255 run five D1 items per wave
# speedup vs baseline: 1.0138x; 1.0085x over previous
; #define D1_LOAD(RH, RV, IT) do { const int it_ = (IT); const int s_ = it_ % 6, m0_ = (it_ / 6) * 16, ch_ = 512 * s_ + 8 * lane; \
;         _Pragma("unroll") for (int tt = 0; tt < 16; ++tt) RV[tt] = *(gcu)(PROJ + (size_t)(m0_ + tt) * NPROJ + ch_); } while (0)
; #define EN(k) if constexpr (((PHASE_MASK) >> (k)) & 1)
; DI void d1_phase(const Params& P, int l, int gw, int NGW, int lane) {
;     ...
;     u32x4 vA[16], vB[16]; int hA = 0, hB = 0; (void)hA; (void)hB;
;     if (gw < NIT) D1_LOAD(hA, vA, gw);
; #pragma unroll 1
;     for (int it = gw; it < NIT; it += 2 * NGW) {
;         if (it + NGW < NIT) D1_LOAD(hB, vB, it + NGW);
; __global__ void __launch_bounds__(512, 2) fwd_kernel(Params PK) {
;     ...
;         case 2: EN(2) d1_phase(P, l, gw, NGW, lane); break;
.LBB0_489:
	s_andn2_b64 vcc, exec, s[0:1]
	s_cbranch_vccnz .LBB0_579
	v_readlane_b32 s0, v252, 0
	s_cmpk_lt_i32 s0, 0x80
	s_cbranch_scc1 .Lg1t_g1entry
	s_add_i32 s0, s0, 0xffffff80
	s_lshl_b32 s0, s0, 3
	s_add_i32 s18, s0, s6
	s_movk_i32 s70, 0x1400
.Lg1t_d1:
	s_movk_i32 s23, 0x400
	s_cmp_lt_i32 s18, s70
	s_cselect_b64 s[0:1], -1, 0
	s_cmp_ge_i32 s18, s70
	s_cbranch_scc1 .LBB0_492
	s_mul_hi_i32 s4, s18, 0x2aaaaaab
	s_lshr_b32 s5, s4, 31
	s_add_i32 s4, s4, s5
	s_mul_i32 s5, s4, 6
	s_sub_i32 s5, s18, s5
	s_waitcnt vmcnt(0)
	v_lshlrev_b32_e32 v0, 3, v240
	s_lshl_b32 s8, s4, 4
	v_lshl_or_b32 v0, s5, 9, v0
	v_readlane_b32 s4, v255, 6
	v_ashrrev_i32_e32 v1, 31, v0
	v_readlane_b32 s5, v255, 7
	s_nop 1
	v_lshl_add_u64 v[56:57], v[0:1], 1, s[4:5]
	v_mad_i64_i32 v[0:1], s[4:5], s8, v237, v[56:57]
	s_or_b32 s4, s8, 1
	s_nop 0
	v_mad_i64_i32 v[4:5], s[4:5], s4, v237, v[56:57]
	s_or_b32 s4, s8, 2
	s_nop 0
	v_mad_i64_i32 v[8:9], s[4:5], s4, v237, v[56:57]
	s_or_b32 s4, s8, 3
	s_nop 0
	v_mad_i64_i32 v[12:13], s[4:5], s4, v237, v[56:57]
	s_or_b32 s4, s8, 4
	s_nop 0
	v_mad_i64_i32 v[16:17], s[4:5], s4, v237, v[56:57]
	s_or_b32 s4, s8, 5
	s_nop 0
	v_mad_i64_i32 v[20:21], s[4:5], s4, v237, v[56:57]
	s_or_b32 s4, s8, 6
	s_nop 0
	v_mad_i64_i32 v[24:25], s[4:5], s4, v237, v[56:57]
	s_or_b32 s4, s8, 7
	s_nop 0
	v_mad_i64_i32 v[28:29], s[4:5], s4, v237, v[56:57]
	s_or_b32 s4, s8, 8
	s_nop 0
	v_mad_i64_i32 v[32:33], s[4:5], s4, v237, v[56:57]
	s_or_b32 s4, s8, 9
	s_nop 0
	v_mad_i64_i32 v[36:37], s[4:5], s4, v237, v[56:57]
	s_or_b32 s4, s8, 10
	s_nop 0
	v_mad_i64_i32 v[40:41], s[4:5], s4, v237, v[56:57]
	s_or_b32 s4, s8, 11
	s_nop 0
	v_mad_i64_i32 v[44:45], s[4:5], s4, v237, v[56:57]
	s_or_b32 s4, s8, 12
	s_nop 0
	v_mad_i64_i32 v[48:49], s[4:5], s4, v237, v[56:57]
	s_or_b32 s4, s8, 13
	s_nop 0
	v_mad_i64_i32 v[52:53], s[4:5], s4, v237, v[56:57]
	s_or_b32 s4, s8, 14
	s_nop 0
	v_mad_i64_i32 v[58:59], s[4:5], s4, v237, v[56:57]
	s_or_b32 s4, s8, 15
	s_nop 0
	v_mad_i64_i32 v[60:61], s[4:5], s4, v237, v[56:57]
	global_load_dwordx4 v[0:3], v[0:1], off
	s_nop 0
	global_load_dwordx4 v[4:7], v[4:5], off
	s_nop 0
	global_load_dwordx4 v[8:11], v[8:9], off
	s_nop 0
	global_load_dwordx4 v[12:15], v[12:13], off
	s_nop 0
	global_load_dwordx4 v[16:19], v[16:17], off
	s_nop 0
	global_load_dwordx4 v[20:23], v[20:21], off
	s_nop 0
	global_load_dwordx4 v[24:27], v[24:25], off
	s_nop 0
	global_load_dwordx4 v[28:31], v[28:29], off
	s_nop 0
	global_load_dwordx4 v[32:35], v[32:33], off
	s_nop 0
	global_load_dwordx4 v[36:39], v[36:37], off
	s_nop 0
	global_load_dwordx4 v[40:43], v[40:41], off
	s_nop 0
	global_load_dwordx4 v[44:47], v[44:45], off
	s_nop 0
	global_load_dwordx4 v[48:51], v[48:49], off
	s_nop 0
	global_load_dwordx4 v[52:55], v[52:53], off
	s_nop 0
	global_load_dwordx4 v[56:59], v[58:59], off
	s_nop 0
	global_load_dwordx4 v[60:63], v[60:61], off
.LBB0_492:
	s_andn2_b64 vcc, exec, s[0:1]
	s_cbranch_vccnz .LBB0_579
	v_readlane_b32 s0, v254, 62
	v_readlane_b32 s1, v254, 63
	s_mov_b32 s4, s0
	v_readlane_b32 s48, v253, 55
	s_mul_i32 s1, s4, 0xc000
	v_readlane_b32 s62, v254, 5
	s_mul_hi_i32 s0, s0, 0xc000
	v_readlane_b32 s63, v254, 6
	s_add_u32 s4, s62, s1
	s_addc_u32 s5, s63, s0
	v_lshlrev_b32_e32 v191, 3, v240
	s_movk_i32 s0, 0x800
	s_waitcnt vmcnt(0)
	v_and_b32_e32 v64, 0x78, v191
	s_lshl_b32 s13, s0, 9
	s_movk_i32 s1, 0x3000
	s_lshl_b32 s12, s18, 9
	v_or_b32_e32 v218, s13, v191
	v_lshlrev_b32_e32 v96, 1, v64
	s_mov_b32 s14, s18
	v_readlane_b32 s49, v253, 56
	v_readlane_b32 s50, v253, 57
	v_readlane_b32 s51, v253, 58
	v_readlane_b32 s52, v253, 59
	v_readlane_b32 s53, v253, 60
	v_readlane_b32 s54, v253, 61
	v_readlane_b32 s55, v253, 62
	v_readlane_b32 s56, v253, 63
	v_readlane_b32 s57, v254, 0
	v_readlane_b32 s58, v254, 1
	v_readlane_b32 s59, v254, 2
	v_readlane_b32 s60, v254, 3
	v_readlane_b32 s61, v254, 4
	s_branch .LBB0_496

; #define D1_LOAD(RH, RV, IT) do { const int it_ = (IT); const int s_ = it_ % 6, m0_ = (it_ / 6) * 16, ch_ = 512 * s_ + 8 * lane; \
;         _Pragma("unroll") for (int tt = 0; tt < 16; ++tt) RV[tt] = *(gcu)(PROJ + (size_t)(m0_ + tt) * NPROJ + ch_); } while (0)
; DI void d1_phase(const Params& P, int l, int gw, int NGW, int lane) {
;     ...
;     for (int it = gw; it < NIT; it += 2 * NGW) {
;         if (it + NGW < NIT) D1_LOAD(hB, vB, it + NGW);
.LBB0_495:
	s_add_i32 s12, s12, s13
	s_cmp_ge_i32 s14, s70
	s_cbranch_scc1 .LBB0_579
.LBB0_496:
	s_add_i32 s19, s23, s14
	s_cmp_lt_i32 s19, s70
	s_cselect_b64 s[40:41], -1, 0
	s_cmp_ge_i32 s19, s70
	s_mul_hi_i32 s15, s19, 0x2aaaaaab
	s_cbranch_scc1 .LBB0_498
	s_lshr_b32 s0, s15, 31
	s_add_i32 s0, s15, s0
	s_mul_i32 s1, s0, 6
	s_sub_i32 s1, s19, s1
	s_lshl_b32 s8, s0, 4
	v_lshl_or_b32 v64, s1, 9, v191
	v_readlane_b32 s0, v255, 6
	v_ashrrev_i32_e32 v65, 31, v64
	v_readlane_b32 s1, v255, 7
	s_nop 1
	v_lshl_add_u64 v[122:123], v[64:65], 1, s[0:1]
	v_mad_i64_i32 v[64:65], s[0:1], s8, v237, v[122:123]
	s_or_b32 s0, s8, 1
	s_nop 0
	v_mad_i64_i32 v[68:69], s[0:1], s0, v237, v[122:123]
	s_or_b32 s0, s8, 2
	s_nop 0
	v_mad_i64_i32 v[72:73], s[0:1], s0, v237, v[122:123]
	s_or_b32 s0, s8, 3
	s_nop 0
	v_mad_i64_i32 v[76:77], s[0:1], s0, v237, v[122:123]
	s_or_b32 s0, s8, 4
	s_nop 0
	v_mad_i64_i32 v[80:81], s[0:1], s0, v237, v[122:123]
	s_or_b32 s0, s8, 5
	s_nop 0
	v_mad_i64_i32 v[84:85], s[0:1], s0, v237, v[122:123]
	s_or_b32 s0, s8, 6
	s_nop 0
	v_mad_i64_i32 v[88:89], s[0:1], s0, v237, v[122:123]
	s_or_b32 s0, s8, 7
	s_nop 0
	v_mad_i64_i32 v[92:93], s[0:1], s0, v237, v[122:123]
	s_or_b32 s0, s8, 8
	s_nop 0
	v_mad_i64_i32 v[98:99], s[0:1], s0, v237, v[122:123]
	s_or_b32 s0, s8, 9
	s_nop 0
	v_mad_i64_i32 v[102:103], s[0:1], s0, v237, v[122:123]
	s_or_b32 s0, s8, 10
	s_nop 0
	v_mad_i64_i32 v[106:107], s[0:1], s0, v237, v[122:123]
	s_or_b32 s0, s8, 11
	s_nop 0
	v_mad_i64_i32 v[110:111], s[0:1], s0, v237, v[122:123]
	s_or_b32 s0, s8, 12
	s_nop 0
	v_mad_i64_i32 v[114:115], s[0:1], s0, v237, v[122:123]
	s_or_b32 s0, s8, 13
	s_nop 0
	v_mad_i64_i32 v[118:119], s[0:1], s0, v237, v[122:123]
	s_or_b32 s0, s8, 14
	s_nop 0
	v_mad_i64_i32 v[124:125], s[0:1], s0, v237, v[122:123]
	s_or_b32 s0, s8, 15
	s_nop 0
	v_mad_i64_i32 v[126:127], s[0:1], s0, v237, v[122:123]
	global_load_dwordx4 v[64:67], v[64:65], off
	s_nop 0
	global_load_dwordx4 v[68:71], v[68:69], off
	s_nop 0
	global_load_dwordx4 v[72:75], v[72:73], off
	s_nop 0
	global_load_dwordx4 v[76:79], v[76:77], off
	s_nop 0
	global_load_dwordx4 v[80:83], v[80:81], off
	s_nop 0
	global_load_dwordx4 v[84:87], v[84:85], off
	s_nop 0
	global_load_dwordx4 v[88:91], v[88:89], off
	s_nop 0
	global_load_dwordx4 v[92:95], v[92:93], off
	s_nop 0
	global_load_dwordx4 v[98:101], v[98:99], off
	s_nop 0
	global_load_dwordx4 v[102:105], v[102:103], off
	s_nop 0
	global_load_dwordx4 v[106:109], v[106:107], off
	s_nop 0
	global_load_dwordx4 v[110:113], v[110:111], off
	s_nop 0
	global_load_dwordx4 v[114:117], v[114:115], off
	s_nop 0
	global_load_dwordx4 v[118:121], v[118:119], off
	s_nop 0
	global_load_dwordx4 v[122:125], v[124:125], off
	s_nop 0
	global_load_dwordx4 v[126:129], v[126:127], off
	s_movk_i32 s1, 0x3000

.LBB0_507:
	v_pk_mul_f32 v[172:173], v[172:173], v[214:215] op_sel_hi:[1,0]
	v_pk_mul_f32 v[184:185], v[150:151], v[208:209]
	v_cvt_pk_bf16_f32 v220, v172, v173
	v_pk_mul_f32 v[172:173], v[202:203], v[214:215] op_sel_hi:[1,0]
	v_pk_fma_f32 v[184:185], v[146:147], v[206:207], v[184:185]
	v_cvt_pk_bf16_f32 v221, v172, v173
	v_pk_mul_f32 v[172:173], v[210:211], v[214:215] op_sel_hi:[1,0]
	v_lshlrev_b32_e32 v210, 16, v4
	v_and_b32_e32 v211, 0xffff0000, v4
	v_pk_fma_f32 v[184:185], v[154:155], v[196:197], v[184:185]
	v_and_b32_e32 v203, 0xffff0000, v5
	v_pk_fma_f32 v[184:185], v[158:159], v[210:211], v[184:185]
	v_lshlrev_b32_e32 v202, 16, v5
	v_mul_f32_e32 v169, 0xbfb8aa3b, v184
	v_exp_f32_e32 v169, v169
	v_lshrrev_b32_e32 v162, 7, v178
	v_and_b32_e32 v179, 0xffff0000, v6
	v_lshlrev_b32_e32 v178, 16, v6
	v_add_f32_e32 v169, 1.0, v169
	v_rcp_f32_e32 v186, v169
	v_mul_f32_e32 v169, 0xbfb8aa3b, v185
	v_exp_f32_e32 v169, v169
	v_cvt_pk_bf16_f32 v222, v172, v173
	v_pk_mul_f32 v[172:173], v[212:213], v[214:215] op_sel_hi:[1,0]
	s_ashr_i32 s0, s11, 9
	v_add_f32_e32 v169, 1.0, v169
	v_rcp_f32_e32 v187, v169
	v_cvt_pk_bf16_f32 v223, v172, v173
	v_and_b32_e32 v173, 0xffff0000, v7
	v_lshlrev_b32_e32 v172, 16, v7
	v_pk_mul_f32 v[206:207], v[184:185], v[186:187]
	v_pk_mul_f32 v[184:185], v[152:153], v[200:201]
	s_add_i32 s11, s0, s20
	v_pk_fma_f32 v[184:185], v[148:149], v[204:205], v[184:185]
	s_cmp_eq_u32 s22, 1
	v_pk_fma_f32 v[184:185], v[156:157], v[174:175], v[184:185]
	s_mov_b32 s0, 0x1f100000
	v_pk_fma_f32 v[184:185], v[160:161], v[202:203], v[184:185]
	s_cselect_b32 s20, 0x1d100000, s0
	v_mul_f32_e32 v169, 0xbfb8aa3b, v184
	v_exp_f32_e32 v169, v169
	s_and_b64 s[0:1], vcc, exec
	s_cselect_b32 s0, 0x1b100000, s20
	v_readlane_b32 s22, v254, 56
	v_add_f32_e32 v169, 1.0, v169
	v_rcp_f32_e32 v186, v169
	v_mul_f32_e32 v169, 0xbfb8aa3b, v185
	v_exp_f32_e32 v169, v169
	v_readlane_b32 s23, v254, 57
	s_add_u32 s0, s22, s0
	s_addc_u32 s1, s23, 0
	v_add_f32_e32 v169, 1.0, v169
	v_rcp_f32_e32 v187, v169
	s_lshl_b32 s11, s11, 3
	v_and_or_b32 v162, v162, 7, s11
	v_ashrrev_i32_e32 v163, 31, v162
	v_pk_mul_f32 v[204:205], v[184:185], v[186:187]
	v_pk_mul_f32 v[184:185], v[134:135], v[198:199]
	s_ashr_i32 s11, s10, 31
	v_pk_fma_f32 v[180:181], v[130:131], v[180:181], v[184:185]
	v_lshlrev_b64 v[162:163], 21, v[162:163]
	v_pk_fma_f32 v[180:181], v[138:139], v[166:167], v[180:181]
	v_lshl_add_u64 v[162:163], s[0:1], 0, v[162:163]
	v_pk_fma_f32 v[180:181], v[142:143], v[178:179], v[180:181]
	s_lshl_b64 s[0:1], s[10:11], 8
	v_mul_f32_e32 v169, 0xbfb8aa3b, v180
	v_exp_f32_e32 v169, v169
	v_lshl_add_u64 v[162:163], v[162:163], 0, s[0:1]
	v_lshl_add_u64 v[162:163], v[162:163], 0, v[96:97]
	s_andn2_b64 vcc, exec, s[8:9]
	v_add_f32_e32 v169, 1.0, v169
	v_rcp_f32_e32 v184, v169
	v_mul_f32_e32 v169, 0xbfb8aa3b, v181
	v_exp_f32_e32 v169, v169
	s_movk_i32 s23, 0x400
	global_store_dwordx4 v[162:163], v[220:223], off
	v_add_f32_e32 v169, 1.0, v169
	v_rcp_f32_e32 v185, v169
	s_nop 0
	v_pk_mul_f32 v[180:181], v[180:181], v[184:185]
	v_pk_mul_f32 v[184:185], v[136:137], v[176:177]
	s_nop 0
	v_pk_fma_f32 v[170:171], v[132:133], v[170:171], v[184:185]
	s_nop 0
	v_pk_fma_f32 v[170:171], v[140:141], v[164:165], v[170:171]
	s_nop 0
	v_pk_fma_f32 v[170:171], v[144:145], v[172:173], v[170:171]
	s_nop 0
	v_mul_f32_e32 v169, 0xbfb8aa3b, v170
	v_exp_f32_e32 v169, v169
	s_nop 0
	v_add_f32_e32 v169, 1.0, v169
	v_rcp_f32_e32 v184, v169
	v_mul_f32_e32 v169, 0xbfb8aa3b, v171
	v_exp_f32_e32 v169, v169
	s_nop 0
	v_add_f32_e32 v169, 1.0, v169
	v_rcp_f32_e32 v185, v169
	v_cndmask_b32_e64 v169, 0, 1, s[8:9]
	v_cmp_ne_u32_e64 s[38:39], 1, v169
	v_pk_mul_f32 v[170:171], v[170:171], v[184:185]
	s_cbranch_vccnz .LBB0_509
	v_pk_mul_f32 v[168:169], v[206:207], v[206:207]
	v_pk_mul_f32 v[184:185], v[204:205], v[204:205]
	v_add_f32_e32 v168, v168, v169
	v_add_f32_e32 v168, v184, v168
	v_pk_mul_f32 v[186:187], v[180:181], v[180:181]
	v_add_f32_e32 v168, v185, v168
	v_and_b32_e32 v184, 64, v232
	v_add_f32_e32 v168, v186, v168
	v_xor_b32_e32 v169, 1, v232
	v_add_u32_e32 v184, 64, v184
	v_pk_mul_f32 v[212:213], v[170:171], v[170:171]
	v_add_f32_e32 v168, v187, v168
	v_cmp_lt_i32_e32 vcc, v169, v184
	v_add_f32_e32 v168, v212, v168
	v_add_f32_e32 v168, v213, v168
	v_cndmask_b32_e32 v169, v232, v169, vcc
	v_lshlrev_b32_e32 v169, 2, v169
	ds_bpermute_b32 v169, v169, v168
	s_waitcnt lgkmcnt(0)
	v_add_f32_e32 v168, v168, v169
	v_xor_b32_e32 v169, 2, v232
	v_cmp_lt_i32_e32 vcc, v169, v184
	s_nop 1
	v_cndmask_b32_e32 v169, v232, v169, vcc
	v_lshlrev_b32_e32 v169, 2, v169
	ds_bpermute_b32 v169, v169, v168
	s_waitcnt lgkmcnt(0)
	v_add_f32_e32 v168, v168, v169
	v_xor_b32_e32 v169, 4, v232
	v_cmp_lt_i32_e32 vcc, v169, v184
	s_nop 1
	v_cndmask_b32_e32 v169, v232, v169, vcc
	v_lshlrev_b32_e32 v169, 2, v169
	ds_bpermute_b32 v169, v169, v168
	s_waitcnt lgkmcnt(0)
	v_add_f32_e32 v168, v168, v169
	v_xor_b32_e32 v169, 8, v232
	v_cmp_lt_i32_e32 vcc, v169, v184
	s_nop 1
	v_cndmask_b32_e32 v169, v232, v169, vcc
	v_lshlrev_b32_e32 v169, 2, v169
	ds_bpermute_b32 v169, v169, v168
	s_waitcnt lgkmcnt(0)
	v_add_f32_e32 v168, v168, v169
	v_add_f32_e32 v168, 0x358637bd, v168
	v_rsq_f32_e32 v168, v168
	s_nop 0
	v_mul_f32_e32 v168, v219, v168

; #define D1_LOAD(RH, RV, IT) do { const int it_ = (IT); const int s_ = it_ % 6, m0_ = (it_ / 6) * 16, ch_ = 512 * s_ + 8 * lane; \
;         _Pragma("unroll") for (int tt = 0; tt < 16; ++tt) RV[tt] = *(gcu)(PROJ + (size_t)(m0_ + tt) * NPROJ + ch_); } while (0)
; DI void d1_phase(const Params& P, int l, int gw, int NGW, int lane) {
;     ...
;     u32x4 vA[16], vB[16]; int hA = 0, hB = 0; (void)hA; (void)hB;
;     if (gw < NIT) D1_LOAD(hA, vA, gw);
; #pragma unroll 1
;     for (int it = gw; it < NIT; it += 2 * NGW) {
;         if (it + NGW < NIT) D1_LOAD(hB, vB, it + NGW);
;         D1_COMPUTE(hA, vA, it);
;         if (it + NGW < NIT) {
;             if (it + 2 * NGW < NIT) D1_LOAD(hA, vA, it + 2 * NGW);
;             D1_COMPUTE(hB, vB, it + NGW);
;         }
.LBB0_537:
	v_pk_mul_f32 v[130:131], v[130:131], v[168:169] op_sel_hi:[1,0]
	v_pk_mul_f32 v[136:137], v[146:147], v[168:169] op_sel_hi:[1,0]
	v_pk_mul_f32 v[132:133], v[132:133], v[168:169] op_sel_hi:[1,0]
	v_cvt_pk_bf16_f32 v138, v130, v131
	v_pk_mul_f32 v[130:131], v[134:135], v[168:169] op_sel_hi:[1,0]
	s_movk_i32 s0, 0x800
	v_cvt_pk_bf16_f32 v136, v136, v137
	v_cvt_pk_bf16_f32 v137, v132, v133
	v_cvt_pk_bf16_f32 v139, v130, v131
	s_andn2_b64 vcc, exec, s[40:41]
	s_add_i32 s14, s14, s0
	global_store_dwordx4 v[162:163], v[136:139], off offset:3840
	s_cbranch_vccnz .LBB0_495
	s_movk_i32 s9, 0x3000
	s_cmp_ge_i32 s14, s70
	s_cbranch_scc1 .LBB0_540
	s_mul_hi_i32 s0, s14, 0x2aaaaaab
	s_lshr_b32 s1, s0, 31
	s_add_i32 s0, s0, s1
	s_lshl_b32 s8, s0, 4
	s_mulk_i32 s0, 0xf400
	s_add_i32 s0, s0, s12
	v_add_u32_e32 v0, s0, v218
	v_readlane_b32 s0, v255, 6
	v_ashrrev_i32_e32 v1, 31, v0
	v_readlane_b32 s1, v255, 7
	s_nop 1
	v_lshl_add_u64 v[56:57], v[0:1], 1, s[0:1]
	v_mad_i64_i32 v[0:1], s[0:1], s8, v237, v[56:57]
	s_or_b32 s0, s8, 1
	s_nop 0
	v_mad_i64_i32 v[4:5], s[0:1], s0, v237, v[56:57]
	s_or_b32 s0, s8, 2
	s_nop 0
	v_mad_i64_i32 v[8:9], s[0:1], s0, v237, v[56:57]
	s_or_b32 s0, s8, 3
	s_nop 0
	v_mad_i64_i32 v[12:13], s[0:1], s0, v237, v[56:57]
	s_or_b32 s0, s8, 4
	s_nop 0
	v_mad_i64_i32 v[16:17], s[0:1], s0, v237, v[56:57]
	s_or_b32 s0, s8, 5
	s_nop 0
	v_mad_i64_i32 v[20:21], s[0:1], s0, v237, v[56:57]
	s_or_b32 s0, s8, 6
	s_nop 0
	v_mad_i64_i32 v[24:25], s[0:1], s0, v237, v[56:57]
	s_or_b32 s0, s8, 7
	s_nop 0
	v_mad_i64_i32 v[28:29], s[0:1], s0, v237, v[56:57]
	s_or_b32 s0, s8, 8
	s_nop 0
	v_mad_i64_i32 v[32:33], s[0:1], s0, v237, v[56:57]
	s_or_b32 s0, s8, 9
	s_nop 0
	v_mad_i64_i32 v[36:37], s[0:1], s0, v237, v[56:57]
	s_or_b32 s0, s8, 10
	s_nop 0
	v_mad_i64_i32 v[40:41], s[0:1], s0, v237, v[56:57]
	s_or_b32 s0, s8, 11
	s_nop 0
	v_mad_i64_i32 v[44:45], s[0:1], s0, v237, v[56:57]
	s_or_b32 s0, s8, 12
	s_nop 0
	v_mad_i64_i32 v[48:49], s[0:1], s0, v237, v[56:57]
	s_or_b32 s0, s8, 13
	s_nop 0
	v_mad_i64_i32 v[52:53], s[0:1], s0, v237, v[56:57]
	s_or_b32 s0, s8, 14
	s_nop 0
	v_mad_i64_i32 v[58:59], s[0:1], s0, v237, v[56:57]
	s_or_b32 s0, s8, 15
	s_nop 0
	v_mad_i64_i32 v[60:61], s[0:1], s0, v237, v[56:57]
	global_load_dwordx4 v[0:3], v[0:1], off
	s_nop 0
	global_load_dwordx4 v[4:7], v[4:5], off
	s_nop 0
	global_load_dwordx4 v[8:11], v[8:9], off
	s_nop 0
	global_load_dwordx4 v[12:15], v[12:13], off
	s_nop 0
	global_load_dwordx4 v[16:19], v[16:17], off
	s_nop 0
	global_load_dwordx4 v[20:23], v[20:21], off
	s_nop 0
	global_load_dwordx4 v[24:27], v[24:25], off
	s_nop 0
	global_load_dwordx4 v[28:31], v[28:29], off
	s_nop 0
	global_load_dwordx4 v[32:35], v[32:33], off
	s_nop 0
	global_load_dwordx4 v[36:39], v[36:37], off
	s_nop 0
	global_load_dwordx4 v[40:43], v[40:41], off
	s_nop 0
	global_load_dwordx4 v[44:47], v[44:45], off
	s_nop 0
	global_load_dwordx4 v[48:51], v[48:49], off
	s_nop 0
	global_load_dwordx4 v[52:55], v[52:53], off
	s_nop 0
	global_load_dwordx4 v[56:59], v[58:59], off
	s_nop 0
	global_load_dwordx4 v[60:63], v[60:61], off

; #define D1_LOAD(RH, RV, IT) do { const int it_ = (IT); const int s_ = it_ % 6, m0_ = (it_ / 6) * 16, ch_ = 512 * s_ + 8 * lane; \
;         _Pragma("unroll") for (int tt = 0; tt < 16; ++tt) RV[tt] = *(gcu)(PROJ + (size_t)(m0_ + tt) * NPROJ + ch_); } while (0)
; DI void d1_phase(const Params& P, int l, int gw, int NGW, int lane) {
;     ...
;     u32x4 vA[16], vB[16]; int hA = 0, hB = 0; (void)hA; (void)hB;
;     if (gw < NIT) D1_LOAD(hA, vA, gw);
; #pragma unroll 1
;     for (int it = gw; it < NIT; it += 2 * NGW) {
;         if (it + NGW < NIT) D1_LOAD(hB, vB, it + NGW);
;         D1_COMPUTE(hA, vA, it);
;         if (it + NGW < NIT) {
;             if (it + 2 * NGW < NIT) D1_LOAD(hA, vA, it + 2 * NGW);
;             D1_COMPUTE(hB, vB, it + NGW);
;         }
;     }
.LBB0_579:
	v_readlane_b32 s23, v254, 48
	s_mov_b64 s[0:1], 0

;     __host__ __device__ bool next(int i, Unit& u) const {
;         const int ii = rev ? (nwg / G - 1 - i) : i; if (ii < 0) return false;
;         const long L = (long)ii * G + c; if (L >= nwg) return false;
;         int wgid = (int)L; { const int q = nwg / NXCD, r = nwg % NXCD, xcd = wgid % NXCD, off = wgid / NXCD; wgid = (xcd < r ? xcd * (q + 1) : r * (q + 1) + (xcd - r) * q) + off; }
;         const int nig = wgm * nN, gid = wgid / nig, fm = gid * wgm, gsz = (nM - fm) < wgm ? (nM - fm) : wgm;
;         u.pm = fm + ((wgid % nig) % gsz); u.pn = (wgid % nig) / gsz; return true;
;     }
; template <class Epi, class Sched, bool ALIGN_EPI = false, bool SP2 = false>
; __device__ __forceinline__ void gemm_phase(PG8_LAS unsigned char* lds, const Gemm g, const Sched& S, const Epi& E, const int tid_in) {
;     ...
;     Unit cur, nxt; int ui = 0;
;     if (!S.next(0, cur)) return;
.Lg1t_g1entry:
	v_readlane_b32 s4, v253, 23
	v_readlane_b32 s5, v253, 24
	s_andn2_b64 vcc, exec, s[4:5]
	v_readfirstlane_b32 s12, v241
	s_waitcnt vmcnt(0)
	v_cndmask_b32_e64 v0, 0, 1, s[4:5]
	v_cmp_ne_u32_e64 s[0:1], 1, v0
	s_cbranch_vccnz .LBB0_584
	v_readlane_b32 s4, v253, 48
	s_mov_b32 s48, s4
	v_readlane_b32 s4, v253, 49
	s_mov_b32 s40, s4
	v_mov_b64_e32 v[192:193], 0x500
	v_mov_b64_e32 v[194:195], 0x4ff
	v_readlane_b32 s4, v255, 8
	s_cmp_eq_u32 s4, 2
	s_cbranch_scc0 .LBB0_584
	v_readlane_b32 s4, v252, 0
	s_lshr_b32 s48, s4, 5
	s_add_i32 s48, s48, 18
	s_and_b32 s40, s4, 7
	s_lshl_b32 s40, s40, 3
	s_bfe_u32 s4, s4, 0x20003
	s_add_i32 s40, s40, s4
	s_add_i32 s40, s40, 4
	v_mov_b64_e32 v[192:193], 0
	v_mov_b64_e32 v[194:195], -1

; #define D1_LOAD(RH, RV, IT) do { const int it_ = (IT); const int s_ = it_ % 6, m0_ = (it_ / 6) * 16, ch_ = 512 * s_ + 8 * lane; \
;         _Pragma("unroll") for (int tt = 0; tt < 16; ++tt) RV[tt] = *(gcu)(PROJ + (size_t)(m0_ + tt) * NPROJ + ch_); } while (0)
; #define EN(k) if constexpr (((PHASE_MASK) >> (k)) & 1)
; DI void d1_phase(const Params& P, int l, int gw, int NGW, int lane) {
;     ...
;     if (gw < NIT) D1_LOAD(hA, vA, gw);
; #pragma unroll 1
;     for (int it = gw; it < NIT; it += 2 * NGW) {
; __global__ void __launch_bounds__(512, 2) fwd_kernel(Params PK) {
;     ...
;         case 1: EN(1) { pg8::Gemm g{ACT, (const bf16_t*)(P.ws + WS_WIN) + (size_t)l * NPROJ * D, M, NPROJ, D}; pg8::StaticOrder S; S.init(M, NPROJ, G, (int)blockIdx.x, WGM_G1);
;             EpiIn E{PROJ, (float*)(P.ws + WS_BA), (const float*)(P.ws + WS_ROPE)};
;             pg8::gemm_phase<EpiIn, pg8::StaticOrder, true, true>(lds, g, S, E, tid); } break;
;         case 2: EN(2) d1_phase(P, l, gw, NGW, lane); break;
.LBB0_700:
	v_readlane_b32 s0, v255, 8
	s_cmp_eq_u32 s0, 2
	s_cbranch_scc0 .Lg1t_noret
	v_readlane_b32 s0, v252, 0
	s_lshl_b32 s0, s0, 3
	s_add_i32 s0, s0, 0x1400
	v_readfirstlane_b32 s1, v241
	s_ashr_i32 s6, s1, 6
	s_add_i32 s18, s0, s6
	s_movk_i32 s70, 0x1800
	s_branch .Lg1t_d1
